# P2 WY solve: in-block forward substitution with coefficient rows prefetched two steps ahead
# speedup vs baseline: 1.0100x; 1.0001x over previous
.LBB0_375:
	s_lshl_b32 s6, s33, 2
	s_add_i32 s7, s6, s13
	v_mov_b32_e32 v18, s7
	ds_read_b128 v[20:23], v18
	ds_read_b128 v[24:27], v18 offset:16
	ds_read_b128 v[28:31], v18 offset:32
	ds_read_b128 v[32:35], v18 offset:48
	ds_read_b128 v[240:243], v18 offset:272
	ds_read_b128 v[244:247], v18 offset:288
	ds_read_b128 v[248:251], v18 offset:304
	ds_read_b128 v[252:255], v18 offset:320
	s_waitcnt lgkmcnt(4)
	v_fma_f32 v1, -v0, v21, v1
	v_fma_f32 v2, -v0, v22, v2
	v_fma_f32 v3, -v0, v23, v3
	v_fma_f32 v4, -v0, v24, v4
	v_fma_f32 v5, -v0, v25, v5
	v_fma_f32 v6, -v0, v26, v6
	v_fma_f32 v7, -v0, v27, v7
	v_fma_f32 v8, -v0, v28, v8
	v_fma_f32 v9, -v0, v29, v9
	v_fma_f32 v10, -v0, v30, v10
	v_fma_f32 v11, -v0, v31, v11
	v_fma_f32 v12, -v0, v32, v12
	v_fma_f32 v13, -v0, v33, v13
	v_fma_f32 v14, -v0, v34, v14
	v_fma_f32 v15, -v0, v35, v15
	ds_read_b128 v[20:23], v18 offset:544
	ds_read_b128 v[24:27], v18 offset:560
	ds_read_b128 v[28:31], v18 offset:576
	ds_read_b128 v[32:35], v18 offset:592
	s_waitcnt lgkmcnt(4)
	v_fma_f32 v2, -v1, v242, v2
	v_fma_f32 v3, -v1, v243, v3
	v_fma_f32 v4, -v1, v244, v4
	v_fma_f32 v5, -v1, v245, v5
	v_fma_f32 v6, -v1, v246, v6
	v_fma_f32 v7, -v1, v247, v7
	v_fma_f32 v8, -v1, v248, v8
	v_fma_f32 v9, -v1, v249, v9
	v_fma_f32 v10, -v1, v250, v10
	v_fma_f32 v11, -v1, v251, v11
	v_fma_f32 v12, -v1, v252, v12
	v_fma_f32 v13, -v1, v253, v13
	v_fma_f32 v14, -v1, v254, v14
	v_fma_f32 v15, -v1, v255, v15
	ds_read_b128 v[244:247], v18 offset:832
	ds_read_b128 v[248:251], v18 offset:848
	ds_read_b128 v[252:255], v18 offset:864
	s_waitcnt lgkmcnt(3)
	v_fma_f32 v3, -v2, v23, v3
	v_fma_f32 v4, -v2, v24, v4
	v_fma_f32 v5, -v2, v25, v5
	v_fma_f32 v6, -v2, v26, v6
	v_fma_f32 v7, -v2, v27, v7
	v_fma_f32 v8, -v2, v28, v8
	v_fma_f32 v9, -v2, v29, v9
	v_fma_f32 v10, -v2, v30, v10
	v_fma_f32 v11, -v2, v31, v11
	v_fma_f32 v12, -v2, v32, v12
	v_fma_f32 v13, -v2, v33, v13
	v_fma_f32 v14, -v2, v34, v14
	v_fma_f32 v15, -v2, v35, v15
	ds_read_b128 v[24:27], v18 offset:1104
	ds_read_b128 v[28:31], v18 offset:1120
	ds_read_b128 v[32:35], v18 offset:1136
	s_waitcnt lgkmcnt(3)
	v_fma_f32 v4, -v3, v244, v4
	v_fma_f32 v5, -v3, v245, v5
	v_fma_f32 v6, -v3, v246, v6
	v_fma_f32 v7, -v3, v247, v7
	v_fma_f32 v8, -v3, v248, v8
	v_fma_f32 v9, -v3, v249, v9
	v_fma_f32 v10, -v3, v250, v10
	v_fma_f32 v11, -v3, v251, v11
	v_fma_f32 v12, -v3, v252, v12
	v_fma_f32 v13, -v3, v253, v13
	v_fma_f32 v14, -v3, v254, v14
	v_fma_f32 v15, -v3, v255, v15
	ds_read_b128 v[244:247], v18 offset:1376
	ds_read_b128 v[248:251], v18 offset:1392
	ds_read_b128 v[252:255], v18 offset:1408
	s_waitcnt lgkmcnt(3)
	v_fma_f32 v5, -v4, v25, v5
	v_fma_f32 v6, -v4, v26, v6
	v_fma_f32 v7, -v4, v27, v7
	v_fma_f32 v8, -v4, v28, v8
	v_fma_f32 v9, -v4, v29, v9
	v_fma_f32 v10, -v4, v30, v10
	v_fma_f32 v11, -v4, v31, v11
	v_fma_f32 v12, -v4, v32, v12
	v_fma_f32 v13, -v4, v33, v13
	v_fma_f32 v14, -v4, v34, v14
	v_fma_f32 v15, -v4, v35, v15
	ds_read_b128 v[24:27], v18 offset:1648
	ds_read_b128 v[28:31], v18 offset:1664
	ds_read_b128 v[32:35], v18 offset:1680
	s_waitcnt lgkmcnt(3)
	v_fma_f32 v6, -v5, v246, v6
	v_fma_f32 v7, -v5, v247, v7
	v_fma_f32 v8, -v5, v248, v8
	v_fma_f32 v9, -v5, v249, v9
	v_fma_f32 v10, -v5, v250, v10
	v_fma_f32 v11, -v5, v251, v11
	v_fma_f32 v12, -v5, v252, v12
	v_fma_f32 v13, -v5, v253, v13
	v_fma_f32 v14, -v5, v254, v14
	v_fma_f32 v15, -v5, v255, v15
	ds_read_b128 v[248:251], v18 offset:1936
	ds_read_b128 v[252:255], v18 offset:1952
	s_waitcnt lgkmcnt(2)
	v_fma_f32 v7, -v6, v27, v7
	v_fma_f32 v8, -v6, v28, v8
	v_fma_f32 v9, -v6, v29, v9
	v_fma_f32 v10, -v6, v30, v10
	v_fma_f32 v11, -v6, v31, v11
	v_fma_f32 v12, -v6, v32, v12
	v_fma_f32 v13, -v6, v33, v13
	v_fma_f32 v14, -v6, v34, v14
	v_fma_f32 v15, -v6, v35, v15
	ds_read_b128 v[28:31], v18 offset:2208
	ds_read_b128 v[32:35], v18 offset:2224
	s_waitcnt lgkmcnt(2)
	v_fma_f32 v8, -v7, v248, v8
	v_fma_f32 v9, -v7, v249, v9
	v_fma_f32 v10, -v7, v250, v10
	v_fma_f32 v11, -v7, v251, v11
	v_fma_f32 v12, -v7, v252, v12
	v_fma_f32 v13, -v7, v253, v13
	v_fma_f32 v14, -v7, v254, v14
	v_fma_f32 v15, -v7, v255, v15
	ds_read_b128 v[248:251], v18 offset:2480
	ds_read_b128 v[252:255], v18 offset:2496
	s_waitcnt lgkmcnt(2)
	v_fma_f32 v9, -v8, v29, v9
	v_fma_f32 v10, -v8, v30, v10
	v_fma_f32 v11, -v8, v31, v11
	v_fma_f32 v12, -v8, v32, v12
	v_fma_f32 v13, -v8, v33, v13
	v_fma_f32 v14, -v8, v34, v14
	v_fma_f32 v15, -v8, v35, v15
	ds_read_b128 v[28:31], v18 offset:2752
	ds_read_b128 v[32:35], v18 offset:2768
	s_waitcnt lgkmcnt(2)
	v_fma_f32 v10, -v9, v250, v10
	v_fma_f32 v11, -v9, v251, v11
	v_fma_f32 v12, -v9, v252, v12
	v_fma_f32 v13, -v9, v253, v13
	v_fma_f32 v14, -v9, v254, v14
	v_fma_f32 v15, -v9, v255, v15
	ds_read_b128 v[252:255], v18 offset:3040
	s_waitcnt lgkmcnt(1)
	v_fma_f32 v11, -v10, v31, v11
	v_fma_f32 v12, -v10, v32, v12
	v_fma_f32 v13, -v10, v33, v13
	v_fma_f32 v14, -v10, v34, v14
	v_fma_f32 v15, -v10, v35, v15
	ds_read_b128 v[32:35], v18 offset:3312
	s_waitcnt lgkmcnt(1)
	v_fma_f32 v12, -v11, v252, v12
	v_fma_f32 v13, -v11, v253, v13
	v_fma_f32 v14, -v11, v254, v14
	v_fma_f32 v15, -v11, v255, v15
	ds_read_b128 v[252:255], v18 offset:3584
	s_waitcnt lgkmcnt(1)
	v_fma_f32 v13, -v12, v33, v13
	v_fma_f32 v14, -v12, v34, v14
	v_fma_f32 v15, -v12, v35, v15
	ds_read_b128 v[32:35], v18 offset:3856
	s_waitcnt lgkmcnt(1)
	v_fma_f32 v14, -v13, v254, v14
	v_fma_f32 v15, -v13, v255, v15
	s_waitcnt lgkmcnt(0)
	v_fma_f32 v15, -v14, v35, v15
	ds_write_b32 v16, v0
	ds_write_b32 v16, v1 offset:528
	ds_write_b32 v16, v2 offset:1056
	ds_write_b32 v16, v3 offset:1584
	ds_write_b32 v16, v4 offset:2112
	ds_write_b32 v16, v5 offset:2640
	ds_write_b32 v16, v6 offset:3168
	ds_write_b32 v16, v7 offset:3696
	ds_write_b32 v16, v8 offset:4224
	ds_write_b32 v16, v9 offset:4752
	ds_write_b32 v16, v10 offset:5280
	ds_write_b32 v16, v11 offset:5808
	ds_write_b32 v16, v12 offset:6336
	ds_write_b32 v16, v13 offset:6864
	ds_write_b32 v16, v14 offset:7392
	ds_write_b32 v16, v15 offset:7920
	s_add_i32 s11, s11, 1
	s_add_i32 s14, s14, 64
	s_add_i32 s8, s8, 16
	s_add_i32 s9, s9, 64
	s_cmp_eq_u32 s11, 4
	s_cbranch_scc1 .LBB0_446
